# in-proj q/k tiles: head-norm gain slices loaded once per unit instead of before each of 16 store steps behind vmcnt(0)
# speedup vs baseline: 1.1254x; 1.0090x over previous
.LBB0_527:
	v_cndmask_b32_e64 v162, 1.0, v224, s[38:39]
	s_andn2_b64 vcc, exec, s[24:25]
	s_and_b32 s68, s42, 4
	s_cbranch_vccnz .LBB0_529
	v_mul_f32_e32 v0, v127, v127
	v_fmac_f32_e32 v0, v126, v126
	v_fmac_f32_e32 v0, v128, v128
	v_fmac_f32_e32 v0, v129, v129
	v_fmac_f32_e32 v0, v122, v122
	v_fmac_f32_e32 v0, v123, v123
	v_fmac_f32_e32 v0, v124, v124
	v_fmac_f32_e32 v0, v125, v125
	v_fmac_f32_e32 v0, v118, v118
	v_fmac_f32_e32 v0, v119, v119
	v_fmac_f32_e32 v0, v120, v120
	v_fmac_f32_e32 v0, v121, v121
	v_pk_mul_f32 v[200:201], v[114:115], v[114:115]
	v_pk_mul_f32 v[160:161], v[116:117], v[116:117]
	v_add_f32_e32 v0, v200, v0
	v_add_f32_e32 v0, v201, v0
	v_add_f32_e32 v0, v160, v0
	v_add_f32_e32 v0, v161, v0
	ds_bpermute_b32 v160, v167, v0
	s_and_b64 s[24:25], s[38:39], exec
	s_cselect_b32 s24, s55, s57
	s_cselect_b32 s25, s54, s56
	v_mov_b32_e32 v161, s24
	s_waitcnt lgkmcnt(0)
	v_add_f32_e32 v0, v0, v160
	ds_bpermute_b32 v160, v168, v0
	s_add_u32 s24, s70, s9
	s_waitcnt lgkmcnt(0)
	v_add_f32_e32 v0, v0, v160
	v_mul_f32_e32 v160, v158, v158
	v_mul_f32_e32 v0, v160, v0
	v_fmamk_f32 v0, v0, 0x3c800000, v214
	v_rsq_f32_e32 v0, v0
	v_mov_b32_e32 v160, s25
	s_addc_u32 s25, s71, 0
	v_lshl_add_u64 v[160:161], v[142:143], 2, v[160:161]
	v_mul_f32_e32 v0, v158, v0
	v_mul_f32_e32 v158, v162, v0
	v_lshl_or_b32 v0, v198, 3, s68
	v_or_b32_e32 v198, s58, v0
	v_ashrrev_i32_e32 v199, 31, v198
	v_lshlrev_b64 v[198:199], 19, v[198:199]
	v_lshl_add_u64 v[198:199], s[24:25], 0, v[198:199]
	v_lshlrev_b32_e32 v0, 7, v197
	v_lshl_add_u64 v[206:207], v[198:199], 0, v[0:1]
	global_load_dwordx4 v[234:237], v[160:161], off
	global_load_dwordx4 v[238:241], v[160:161], off offset:16
	global_load_dwordx4 v[242:245], v[160:161], off offset:128
	global_load_dwordx4 v[246:249], v[160:161], off offset:144
	s_waitcnt vmcnt(0)
	s_nop 1
	v_mov_b32_e32 v198, v238
	v_mov_b32_e32 v199, v239
	v_mov_b32_e32 v200, v240
	v_mov_b32_e32 v201, v241
	v_mov_b32_e32 v202, v234
	v_mov_b32_e32 v203, v235
	v_mov_b32_e32 v204, v236
	v_mov_b32_e32 v205, v237
	v_pk_mul_f32 v[200:201], v[200:201], v[158:159] op_sel_hi:[1,0]
	v_pk_mul_f32 v[204:205], v[204:205], v[158:159] op_sel_hi:[1,0]
	v_pk_mul_f32 v[202:203], v[202:203], v[158:159] op_sel_hi:[1,0]
	v_pk_mul_f32 v[198:199], v[198:199], v[158:159] op_sel_hi:[1,0]
	v_pk_mul_f32 v[128:129], v[128:129], v[204:205]
	v_pk_mul_f32 v[126:127], v[126:127], v[202:203]
	v_pk_mul_f32 v[200:201], v[124:125], v[200:201]
	v_pk_mul_f32 v[124:125], v[122:123], v[198:199]
	v_lshl_add_u64 v[198:199], v[142:143], 1, v[206:207]
	v_cvt_pk_bf16_f32 v122, v126, v127
	v_cvt_pk_bf16_f32 v123, v128, v129
	v_cvt_pk_bf16_f32 v124, v124, v125
	v_cvt_pk_bf16_f32 v125, v200, v201
	global_store_dwordx4 v[198:199], v[122:125], off
	s_nop 1
	v_mov_b32_e32 v122, v246
	v_mov_b32_e32 v123, v247
	v_mov_b32_e32 v124, v248
	v_mov_b32_e32 v125, v249
	v_mov_b32_e32 v126, v242
	v_mov_b32_e32 v127, v243
	v_mov_b32_e32 v128, v244
	v_mov_b32_e32 v129, v245
	v_pk_mul_f32 v[124:125], v[124:125], v[158:159] op_sel_hi:[1,0]
	v_pk_mul_f32 v[128:129], v[128:129], v[158:159] op_sel_hi:[1,0]
	v_pk_mul_f32 v[126:127], v[126:127], v[158:159] op_sel_hi:[1,0]
	v_pk_mul_f32 v[122:123], v[122:123], v[158:159] op_sel_hi:[1,0]
	v_pk_mul_f32 v[120:121], v[120:121], v[128:129]
	v_pk_mul_f32 v[118:119], v[118:119], v[126:127]
	v_pk_mul_f32 v[124:125], v[116:117], v[124:125]
	v_pk_mul_f32 v[116:117], v[114:115], v[122:123]
	v_cvt_pk_bf16_f32 v114, v118, v119
	v_cvt_pk_bf16_f32 v115, v120, v121
	v_cvt_pk_bf16_f32 v116, v116, v117
	v_cvt_pk_bf16_f32 v117, v124, v125
	global_store_dwordx4 v[198:199], v[114:117], off offset:64

.LBB0_555:
	s_andn2_b64 vcc, exec, s[24:25]
	s_cbranch_vccnz .LBB0_557
	v_mul_f32_e32 v0, v111, v111
	v_fmac_f32_e32 v0, v110, v110
	v_fmac_f32_e32 v0, v112, v112
	v_fmac_f32_e32 v0, v113, v113
	v_fmac_f32_e32 v0, v106, v106
	v_fmac_f32_e32 v0, v107, v107
	v_fmac_f32_e32 v0, v108, v108
	v_fmac_f32_e32 v0, v109, v109
	v_fmac_f32_e32 v0, v102, v102
	v_fmac_f32_e32 v0, v103, v103
	v_fmac_f32_e32 v0, v104, v104
	v_fmac_f32_e32 v0, v105, v105
	v_pk_mul_f32 v[120:121], v[98:99], v[98:99]
	v_pk_mul_f32 v[116:117], v[100:101], v[100:101]
	v_add_f32_e32 v0, v120, v0
	v_add_f32_e32 v0, v121, v0
	v_add_f32_e32 v0, v116, v0
	v_add_f32_e32 v0, v117, v0
	ds_bpermute_b32 v116, v167, v0
	s_and_b64 s[20:21], s[38:39], exec
	s_cselect_b32 s20, s55, s57
	s_cselect_b32 s21, s54, s56
	v_mov_b32_e32 v117, s20
	s_waitcnt lgkmcnt(0)
	v_add_f32_e32 v0, v0, v116
	ds_bpermute_b32 v116, v168, v0
	s_add_u32 s20, s70, s9
	s_waitcnt lgkmcnt(0)
	v_add_f32_e32 v0, v0, v116
	v_mul_f32_e32 v116, v114, v114
	v_mul_f32_e32 v0, v116, v0
	v_fmamk_f32 v0, v0, 0x3c800000, v214
	v_rsq_f32_e32 v0, v0
	v_mov_b32_e32 v116, s21
	s_addc_u32 s21, s71, 0
	v_lshl_add_u64 v[116:117], v[142:143], 2, v[116:117]
	v_mul_f32_e32 v0, v114, v0
	v_mul_f32_e32 v114, v162, v0
	v_lshl_or_b32 v0, v118, 3, s68
	v_or_b32_e32 v118, s58, v0
	v_ashrrev_i32_e32 v119, 31, v118
	v_lshlrev_b64 v[118:119], 19, v[118:119]
	v_lshl_add_u64 v[118:119], s[20:21], 0, v[118:119]
	v_lshlrev_b32_e32 v0, 7, v115
	v_lshl_add_u64 v[126:127], v[118:119], 0, v[0:1]
	s_nop 1
	v_mov_b32_e32 v118, v238
	v_mov_b32_e32 v119, v239
	v_mov_b32_e32 v120, v240
	v_mov_b32_e32 v121, v241
	v_mov_b32_e32 v122, v234
	v_mov_b32_e32 v123, v235
	v_mov_b32_e32 v124, v236
	v_mov_b32_e32 v125, v237
	v_pk_mul_f32 v[120:121], v[120:121], v[114:115] op_sel_hi:[1,0]
	v_pk_mul_f32 v[124:125], v[124:125], v[114:115] op_sel_hi:[1,0]
	v_pk_mul_f32 v[122:123], v[122:123], v[114:115] op_sel_hi:[1,0]
	v_pk_mul_f32 v[118:119], v[118:119], v[114:115] op_sel_hi:[1,0]
	v_pk_mul_f32 v[112:113], v[112:113], v[124:125]
	v_pk_mul_f32 v[110:111], v[110:111], v[122:123]
	v_pk_mul_f32 v[120:121], v[108:109], v[120:121]
	v_pk_mul_f32 v[108:109], v[106:107], v[118:119]
	v_lshl_add_u64 v[118:119], v[142:143], 1, v[126:127]
	v_cvt_pk_bf16_f32 v106, v110, v111
	v_cvt_pk_bf16_f32 v107, v112, v113
	v_cvt_pk_bf16_f32 v108, v108, v109
	v_cvt_pk_bf16_f32 v109, v120, v121
	global_store_dwordx4 v[118:119], v[106:109], off
	s_nop 1
	v_mov_b32_e32 v106, v246
	v_mov_b32_e32 v107, v247
	v_mov_b32_e32 v108, v248
	v_mov_b32_e32 v109, v249
	v_mov_b32_e32 v110, v242
	v_mov_b32_e32 v111, v243
	v_mov_b32_e32 v112, v244
	v_mov_b32_e32 v113, v245
	v_pk_mul_f32 v[108:109], v[108:109], v[114:115] op_sel_hi:[1,0]
	v_pk_mul_f32 v[112:113], v[112:113], v[114:115] op_sel_hi:[1,0]
	v_pk_mul_f32 v[110:111], v[110:111], v[114:115] op_sel_hi:[1,0]
	v_pk_mul_f32 v[106:107], v[106:107], v[114:115] op_sel_hi:[1,0]
	v_pk_mul_f32 v[104:105], v[104:105], v[112:113]
	v_pk_mul_f32 v[102:103], v[102:103], v[110:111]
	v_pk_mul_f32 v[108:109], v[100:101], v[108:109]
	v_pk_mul_f32 v[100:101], v[98:99], v[106:107]
	v_cvt_pk_bf16_f32 v98, v102, v103
	v_cvt_pk_bf16_f32 v99, v104, v105
	v_cvt_pk_bf16_f32 v100, v100, v101
	v_cvt_pk_bf16_f32 v101, v108, v109
	global_store_dwordx4 v[118:119], v[98:101], off offset:64

.LBB0_583:
	s_andn2_b64 vcc, exec, s[20:21]
	s_cbranch_vccnz .LBB0_585
	v_mul_f32_e32 v0, v95, v95
	v_fmac_f32_e32 v0, v94, v94
	v_fmac_f32_e32 v0, v96, v96
	v_fmac_f32_e32 v0, v97, v97
	v_fmac_f32_e32 v0, v90, v90
	v_fmac_f32_e32 v0, v91, v91
	v_fmac_f32_e32 v0, v92, v92
	v_fmac_f32_e32 v0, v93, v93
	v_fmac_f32_e32 v0, v86, v86
	v_fmac_f32_e32 v0, v87, v87
	v_fmac_f32_e32 v0, v88, v88
	v_fmac_f32_e32 v0, v89, v89
	v_pk_mul_f32 v[104:105], v[82:83], v[82:83]
	v_pk_mul_f32 v[100:101], v[84:85], v[84:85]
	v_add_f32_e32 v0, v104, v0
	v_add_f32_e32 v0, v105, v0
	v_add_f32_e32 v0, v100, v0
	v_add_f32_e32 v0, v101, v0
	ds_bpermute_b32 v100, v167, v0
	s_and_b64 s[20:21], s[38:39], exec
	s_cselect_b32 s20, s55, s57
	s_cselect_b32 s21, s54, s56
	v_mov_b32_e32 v101, s20
	s_waitcnt lgkmcnt(0)
	v_add_f32_e32 v0, v0, v100
	ds_bpermute_b32 v100, v168, v0
	s_add_u32 s20, s70, s9
	s_waitcnt lgkmcnt(0)
	v_add_f32_e32 v0, v0, v100
	v_mul_f32_e32 v100, v98, v98
	v_mul_f32_e32 v0, v100, v0
	v_fmamk_f32 v0, v0, 0x3c800000, v214
	v_rsq_f32_e32 v0, v0
	v_mov_b32_e32 v100, s21
	s_addc_u32 s21, s71, 0
	v_lshl_add_u64 v[100:101], v[142:143], 2, v[100:101]
	v_mul_f32_e32 v0, v98, v0
	v_mul_f32_e32 v98, v162, v0
	v_lshl_or_b32 v0, v102, 3, s68
	v_or_b32_e32 v102, s58, v0
	v_ashrrev_i32_e32 v103, 31, v102
	v_lshlrev_b64 v[102:103], 19, v[102:103]
	v_lshl_add_u64 v[102:103], s[20:21], 0, v[102:103]
	v_lshlrev_b32_e32 v0, 7, v99
	v_lshl_add_u64 v[110:111], v[102:103], 0, v[0:1]
	s_nop 1
	v_mov_b32_e32 v102, v238
	v_mov_b32_e32 v103, v239
	v_mov_b32_e32 v104, v240
	v_mov_b32_e32 v105, v241
	v_mov_b32_e32 v106, v234
	v_mov_b32_e32 v107, v235
	v_mov_b32_e32 v108, v236
	v_mov_b32_e32 v109, v237
	v_pk_mul_f32 v[104:105], v[104:105], v[98:99] op_sel_hi:[1,0]
	v_pk_mul_f32 v[108:109], v[108:109], v[98:99] op_sel_hi:[1,0]
	v_pk_mul_f32 v[106:107], v[106:107], v[98:99] op_sel_hi:[1,0]
	v_pk_mul_f32 v[102:103], v[102:103], v[98:99] op_sel_hi:[1,0]
	v_pk_mul_f32 v[96:97], v[96:97], v[108:109]
	v_pk_mul_f32 v[94:95], v[94:95], v[106:107]
	v_pk_mul_f32 v[104:105], v[92:93], v[104:105]
	v_pk_mul_f32 v[92:93], v[90:91], v[102:103]
	v_lshl_add_u64 v[102:103], v[142:143], 1, v[110:111]
	v_cvt_pk_bf16_f32 v90, v94, v95
	v_cvt_pk_bf16_f32 v91, v96, v97
	v_cvt_pk_bf16_f32 v92, v92, v93
	v_cvt_pk_bf16_f32 v93, v104, v105
	global_store_dwordx4 v[102:103], v[90:93], off
	s_nop 1
	v_mov_b32_e32 v90, v246
	v_mov_b32_e32 v91, v247
	v_mov_b32_e32 v92, v248
	v_mov_b32_e32 v93, v249
	v_mov_b32_e32 v94, v242
	v_mov_b32_e32 v95, v243
	v_mov_b32_e32 v96, v244
	v_mov_b32_e32 v97, v245
	v_pk_mul_f32 v[92:93], v[92:93], v[98:99] op_sel_hi:[1,0]
	v_pk_mul_f32 v[96:97], v[96:97], v[98:99] op_sel_hi:[1,0]
	v_pk_mul_f32 v[94:95], v[94:95], v[98:99] op_sel_hi:[1,0]
	v_pk_mul_f32 v[90:91], v[90:91], v[98:99] op_sel_hi:[1,0]
	v_pk_mul_f32 v[88:89], v[88:89], v[96:97]
	v_pk_mul_f32 v[86:87], v[86:87], v[94:95]
	v_pk_mul_f32 v[92:93], v[84:85], v[92:93]
	v_pk_mul_f32 v[84:85], v[82:83], v[90:91]
	v_cvt_pk_bf16_f32 v82, v86, v87
	v_cvt_pk_bf16_f32 v83, v88, v89
	v_cvt_pk_bf16_f32 v84, v84, v85
	v_cvt_pk_bf16_f32 v85, v92, v93
	global_store_dwordx4 v[102:103], v[82:85], off offset:64

.LBB0_611:
	s_andn2_b64 vcc, exec, s[20:21]
	s_cbranch_vccnz .LBB0_613
	v_mul_f32_e32 v0, v79, v79
	v_fmac_f32_e32 v0, v78, v78
	v_fmac_f32_e32 v0, v80, v80
	v_fmac_f32_e32 v0, v81, v81
	v_fmac_f32_e32 v0, v74, v74
	v_fmac_f32_e32 v0, v75, v75
	v_fmac_f32_e32 v0, v76, v76
	v_fmac_f32_e32 v0, v77, v77
	v_fmac_f32_e32 v0, v70, v70
	v_fmac_f32_e32 v0, v71, v71
	v_fmac_f32_e32 v0, v72, v72
	v_fmac_f32_e32 v0, v73, v73
	v_pk_mul_f32 v[88:89], v[66:67], v[66:67]
	v_pk_mul_f32 v[84:85], v[68:69], v[68:69]
	v_add_f32_e32 v0, v88, v0
	v_add_f32_e32 v0, v89, v0
	v_add_f32_e32 v0, v84, v0
	v_add_f32_e32 v0, v85, v0
	ds_bpermute_b32 v84, v167, v0
	s_and_b64 s[20:21], s[38:39], exec
	s_cselect_b32 s20, s55, s57
	s_cselect_b32 s21, s54, s56
	v_mov_b32_e32 v85, s20
	s_waitcnt lgkmcnt(0)
	v_add_f32_e32 v0, v0, v84
	ds_bpermute_b32 v84, v168, v0
	s_add_u32 s20, s70, s9
	s_waitcnt lgkmcnt(0)
	v_add_f32_e32 v0, v0, v84
	v_mul_f32_e32 v84, v82, v82
	v_mul_f32_e32 v0, v84, v0
	v_fmamk_f32 v0, v0, 0x3c800000, v214
	v_rsq_f32_e32 v0, v0
	v_mov_b32_e32 v84, s21
	s_addc_u32 s21, s71, 0
	v_lshl_add_u64 v[84:85], v[142:143], 2, v[84:85]
	v_mul_f32_e32 v0, v82, v0
	v_mul_f32_e32 v82, v162, v0
	v_lshl_or_b32 v0, v86, 3, s68
	v_or_b32_e32 v86, s58, v0
	v_ashrrev_i32_e32 v87, 31, v86
	v_lshlrev_b64 v[86:87], 19, v[86:87]
	v_lshl_add_u64 v[86:87], s[20:21], 0, v[86:87]
	v_lshlrev_b32_e32 v0, 7, v83
	v_lshl_add_u64 v[94:95], v[86:87], 0, v[0:1]
	s_nop 1
	v_mov_b32_e32 v86, v238
	v_mov_b32_e32 v87, v239
	v_mov_b32_e32 v88, v240
	v_mov_b32_e32 v89, v241
	v_mov_b32_e32 v90, v234
	v_mov_b32_e32 v91, v235
	v_mov_b32_e32 v92, v236
	v_mov_b32_e32 v93, v237
	v_pk_mul_f32 v[88:89], v[88:89], v[82:83] op_sel_hi:[1,0]
	v_pk_mul_f32 v[92:93], v[92:93], v[82:83] op_sel_hi:[1,0]
	v_pk_mul_f32 v[90:91], v[90:91], v[82:83] op_sel_hi:[1,0]
	v_pk_mul_f32 v[86:87], v[86:87], v[82:83] op_sel_hi:[1,0]
	v_pk_mul_f32 v[80:81], v[80:81], v[92:93]
	v_pk_mul_f32 v[78:79], v[78:79], v[90:91]
	v_pk_mul_f32 v[88:89], v[76:77], v[88:89]
	v_pk_mul_f32 v[76:77], v[74:75], v[86:87]
	v_lshl_add_u64 v[86:87], v[142:143], 1, v[94:95]
	v_cvt_pk_bf16_f32 v74, v78, v79
	v_cvt_pk_bf16_f32 v75, v80, v81
	v_cvt_pk_bf16_f32 v76, v76, v77
	v_cvt_pk_bf16_f32 v77, v88, v89
	global_store_dwordx4 v[86:87], v[74:77], off
	s_nop 1
	v_mov_b32_e32 v74, v246
	v_mov_b32_e32 v75, v247
	v_mov_b32_e32 v76, v248
	v_mov_b32_e32 v77, v249
	v_mov_b32_e32 v78, v242
	v_mov_b32_e32 v79, v243
	v_mov_b32_e32 v80, v244
	v_mov_b32_e32 v81, v245
	v_pk_mul_f32 v[76:77], v[76:77], v[82:83] op_sel_hi:[1,0]
	v_pk_mul_f32 v[80:81], v[80:81], v[82:83] op_sel_hi:[1,0]
	v_pk_mul_f32 v[78:79], v[78:79], v[82:83] op_sel_hi:[1,0]
	v_pk_mul_f32 v[74:75], v[74:75], v[82:83] op_sel_hi:[1,0]
	v_pk_mul_f32 v[72:73], v[72:73], v[80:81]
	v_pk_mul_f32 v[70:71], v[70:71], v[78:79]
	v_pk_mul_f32 v[76:77], v[68:69], v[76:77]
	v_pk_mul_f32 v[68:69], v[66:67], v[74:75]
	v_cvt_pk_bf16_f32 v66, v70, v71
	v_cvt_pk_bf16_f32 v67, v72, v73
	v_cvt_pk_bf16_f32 v68, v68, v69
	v_cvt_pk_bf16_f32 v69, v76, v77
	global_store_dwordx4 v[86:87], v[66:69], off offset:64

.LBB0_639:
	s_andn2_b64 vcc, exec, s[20:21]
	s_cbranch_vccnz .LBB0_641
	v_mul_f32_e32 v0, v63, v63
	v_fmac_f32_e32 v0, v62, v62
	v_fmac_f32_e32 v0, v64, v64
	v_fmac_f32_e32 v0, v65, v65
	v_fmac_f32_e32 v0, v58, v58
	v_fmac_f32_e32 v0, v59, v59
	v_fmac_f32_e32 v0, v60, v60
	v_fmac_f32_e32 v0, v61, v61
	v_fmac_f32_e32 v0, v54, v54
	v_fmac_f32_e32 v0, v55, v55
	v_fmac_f32_e32 v0, v56, v56
	v_fmac_f32_e32 v0, v57, v57
	v_pk_mul_f32 v[72:73], v[50:51], v[50:51]
	v_pk_mul_f32 v[68:69], v[52:53], v[52:53]
	v_add_f32_e32 v0, v72, v0
	v_add_f32_e32 v0, v73, v0
	v_add_f32_e32 v0, v68, v0
	v_add_f32_e32 v0, v69, v0
	ds_bpermute_b32 v68, v167, v0
	s_and_b64 s[20:21], s[38:39], exec
	s_cselect_b32 s20, s55, s57
	s_cselect_b32 s21, s54, s56
	v_mov_b32_e32 v69, s20
	s_waitcnt lgkmcnt(0)
	v_add_f32_e32 v0, v0, v68
	ds_bpermute_b32 v68, v168, v0
	s_add_u32 s20, s70, s9
	s_waitcnt lgkmcnt(0)
	v_add_f32_e32 v0, v0, v68
	v_mul_f32_e32 v68, v66, v66
	v_mul_f32_e32 v0, v68, v0
	v_fmamk_f32 v0, v0, 0x3c800000, v214
	v_rsq_f32_e32 v0, v0
	v_mov_b32_e32 v68, s21
	s_addc_u32 s21, s71, 0
	v_lshl_add_u64 v[68:69], v[142:143], 2, v[68:69]
	v_mul_f32_e32 v0, v66, v0
	v_mul_f32_e32 v66, v162, v0
	v_lshl_or_b32 v0, v70, 3, s68
	v_or_b32_e32 v70, s58, v0
	v_ashrrev_i32_e32 v71, 31, v70
	v_lshlrev_b64 v[70:71], 19, v[70:71]
	v_lshl_add_u64 v[70:71], s[20:21], 0, v[70:71]
	v_lshlrev_b32_e32 v0, 7, v67
	v_lshl_add_u64 v[78:79], v[70:71], 0, v[0:1]
	s_nop 1
	v_mov_b32_e32 v70, v238
	v_mov_b32_e32 v71, v239
	v_mov_b32_e32 v72, v240
	v_mov_b32_e32 v73, v241
	v_mov_b32_e32 v74, v234
	v_mov_b32_e32 v75, v235
	v_mov_b32_e32 v76, v236
	v_mov_b32_e32 v77, v237
	v_pk_mul_f32 v[72:73], v[72:73], v[66:67] op_sel_hi:[1,0]
	v_pk_mul_f32 v[76:77], v[76:77], v[66:67] op_sel_hi:[1,0]
	v_pk_mul_f32 v[74:75], v[74:75], v[66:67] op_sel_hi:[1,0]
	v_pk_mul_f32 v[70:71], v[70:71], v[66:67] op_sel_hi:[1,0]
	v_pk_mul_f32 v[64:65], v[64:65], v[76:77]
	v_pk_mul_f32 v[62:63], v[62:63], v[74:75]
	v_pk_mul_f32 v[72:73], v[60:61], v[72:73]
	v_pk_mul_f32 v[60:61], v[58:59], v[70:71]
	v_lshl_add_u64 v[70:71], v[142:143], 1, v[78:79]
	v_cvt_pk_bf16_f32 v58, v62, v63
	v_cvt_pk_bf16_f32 v59, v64, v65
	v_cvt_pk_bf16_f32 v60, v60, v61
	v_cvt_pk_bf16_f32 v61, v72, v73
	global_store_dwordx4 v[70:71], v[58:61], off
	s_nop 1
	v_mov_b32_e32 v58, v246
	v_mov_b32_e32 v59, v247
	v_mov_b32_e32 v60, v248
	v_mov_b32_e32 v61, v249
	v_mov_b32_e32 v62, v242
	v_mov_b32_e32 v63, v243
	v_mov_b32_e32 v64, v244
	v_mov_b32_e32 v65, v245
	v_pk_mul_f32 v[60:61], v[60:61], v[66:67] op_sel_hi:[1,0]
	v_pk_mul_f32 v[64:65], v[64:65], v[66:67] op_sel_hi:[1,0]
	v_pk_mul_f32 v[62:63], v[62:63], v[66:67] op_sel_hi:[1,0]
	v_pk_mul_f32 v[58:59], v[58:59], v[66:67] op_sel_hi:[1,0]
	v_pk_mul_f32 v[56:57], v[56:57], v[64:65]
	v_pk_mul_f32 v[54:55], v[54:55], v[62:63]
	v_pk_mul_f32 v[60:61], v[52:53], v[60:61]
	v_pk_mul_f32 v[52:53], v[50:51], v[58:59]
	v_cvt_pk_bf16_f32 v50, v54, v55
	v_cvt_pk_bf16_f32 v51, v56, v57
	v_cvt_pk_bf16_f32 v52, v52, v53
	v_cvt_pk_bf16_f32 v53, v60, v61
	global_store_dwordx4 v[70:71], v[50:53], off offset:64

.LBB0_667:
	s_andn2_b64 vcc, exec, s[20:21]
	s_cbranch_vccnz .LBB0_669
	v_mul_f32_e32 v0, v47, v47
	v_fmac_f32_e32 v0, v46, v46
	v_fmac_f32_e32 v0, v48, v48
	v_fmac_f32_e32 v0, v49, v49
	v_fmac_f32_e32 v0, v42, v42
	v_fmac_f32_e32 v0, v43, v43
	v_fmac_f32_e32 v0, v44, v44
	v_fmac_f32_e32 v0, v45, v45
	v_fmac_f32_e32 v0, v38, v38
	v_fmac_f32_e32 v0, v39, v39
	v_fmac_f32_e32 v0, v40, v40
	v_fmac_f32_e32 v0, v41, v41
	v_pk_mul_f32 v[56:57], v[34:35], v[34:35]
	v_pk_mul_f32 v[52:53], v[36:37], v[36:37]
	v_add_f32_e32 v0, v56, v0
	v_add_f32_e32 v0, v57, v0
	v_add_f32_e32 v0, v52, v0
	v_add_f32_e32 v0, v53, v0
	ds_bpermute_b32 v52, v167, v0
	s_and_b64 s[20:21], s[38:39], exec
	s_cselect_b32 s20, s55, s57
	s_cselect_b32 s21, s54, s56
	v_mov_b32_e32 v53, s20
	s_waitcnt lgkmcnt(0)
	v_add_f32_e32 v0, v0, v52
	ds_bpermute_b32 v52, v168, v0
	s_add_u32 s20, s70, s9
	s_waitcnt lgkmcnt(0)
	v_add_f32_e32 v0, v0, v52
	v_mul_f32_e32 v52, v50, v50
	v_mul_f32_e32 v0, v52, v0
	v_fmamk_f32 v0, v0, 0x3c800000, v214
	v_rsq_f32_e32 v0, v0
	v_mov_b32_e32 v52, s21
	s_addc_u32 s21, s71, 0
	v_lshl_add_u64 v[52:53], v[142:143], 2, v[52:53]
	v_mul_f32_e32 v0, v50, v0
	v_mul_f32_e32 v50, v162, v0
	v_lshl_or_b32 v0, v54, 3, s68
	v_or_b32_e32 v54, s58, v0
	v_ashrrev_i32_e32 v55, 31, v54
	v_lshlrev_b64 v[54:55], 19, v[54:55]
	v_lshl_add_u64 v[54:55], s[20:21], 0, v[54:55]
	v_lshlrev_b32_e32 v0, 7, v51
	v_lshl_add_u64 v[62:63], v[54:55], 0, v[0:1]
	s_nop 1
	v_mov_b32_e32 v54, v238
	v_mov_b32_e32 v55, v239
	v_mov_b32_e32 v56, v240
	v_mov_b32_e32 v57, v241
	v_mov_b32_e32 v58, v234
	v_mov_b32_e32 v59, v235
	v_mov_b32_e32 v60, v236
	v_mov_b32_e32 v61, v237
	v_pk_mul_f32 v[56:57], v[56:57], v[50:51] op_sel_hi:[1,0]
	v_pk_mul_f32 v[60:61], v[60:61], v[50:51] op_sel_hi:[1,0]
	v_pk_mul_f32 v[58:59], v[58:59], v[50:51] op_sel_hi:[1,0]
	v_pk_mul_f32 v[54:55], v[54:55], v[50:51] op_sel_hi:[1,0]
	v_pk_mul_f32 v[48:49], v[48:49], v[60:61]
	v_pk_mul_f32 v[46:47], v[46:47], v[58:59]
	v_pk_mul_f32 v[56:57], v[44:45], v[56:57]
	v_pk_mul_f32 v[44:45], v[42:43], v[54:55]
	v_lshl_add_u64 v[54:55], v[142:143], 1, v[62:63]
	v_cvt_pk_bf16_f32 v42, v46, v47
	v_cvt_pk_bf16_f32 v43, v48, v49
	v_cvt_pk_bf16_f32 v44, v44, v45
	v_cvt_pk_bf16_f32 v45, v56, v57
	global_store_dwordx4 v[54:55], v[42:45], off
	s_nop 1
	v_mov_b32_e32 v42, v246
	v_mov_b32_e32 v43, v247
	v_mov_b32_e32 v44, v248
	v_mov_b32_e32 v45, v249
	v_mov_b32_e32 v46, v242
	v_mov_b32_e32 v47, v243
	v_mov_b32_e32 v48, v244
	v_mov_b32_e32 v49, v245
	v_pk_mul_f32 v[44:45], v[44:45], v[50:51] op_sel_hi:[1,0]
	v_pk_mul_f32 v[48:49], v[48:49], v[50:51] op_sel_hi:[1,0]
	v_pk_mul_f32 v[46:47], v[46:47], v[50:51] op_sel_hi:[1,0]
	v_pk_mul_f32 v[42:43], v[42:43], v[50:51] op_sel_hi:[1,0]
	v_pk_mul_f32 v[40:41], v[40:41], v[48:49]
	v_pk_mul_f32 v[38:39], v[38:39], v[46:47]
	v_pk_mul_f32 v[44:45], v[36:37], v[44:45]
	v_pk_mul_f32 v[36:37], v[34:35], v[42:43]
	v_cvt_pk_bf16_f32 v34, v38, v39
	v_cvt_pk_bf16_f32 v35, v40, v41
	v_cvt_pk_bf16_f32 v36, v36, v37
	v_cvt_pk_bf16_f32 v37, v44, v45
	global_store_dwordx4 v[54:55], v[34:37], off offset:64

.LBB0_695:
	s_andn2_b64 vcc, exec, s[20:21]
	s_cbranch_vccnz .LBB0_697
	v_mul_f32_e32 v0, v31, v31
	v_fmac_f32_e32 v0, v30, v30
	v_fmac_f32_e32 v0, v32, v32
	v_fmac_f32_e32 v0, v33, v33
	v_fmac_f32_e32 v0, v26, v26
	v_fmac_f32_e32 v0, v27, v27
	v_fmac_f32_e32 v0, v28, v28
	v_fmac_f32_e32 v0, v29, v29
	v_fmac_f32_e32 v0, v22, v22
	v_fmac_f32_e32 v0, v23, v23
	v_fmac_f32_e32 v0, v24, v24
	v_fmac_f32_e32 v0, v25, v25
	v_pk_mul_f32 v[40:41], v[18:19], v[18:19]
	v_pk_mul_f32 v[36:37], v[20:21], v[20:21]
	v_add_f32_e32 v0, v40, v0
	v_add_f32_e32 v0, v41, v0
	v_add_f32_e32 v0, v36, v0
	v_add_f32_e32 v0, v37, v0
	ds_bpermute_b32 v36, v167, v0
	s_and_b64 s[20:21], s[38:39], exec
	s_cselect_b32 s20, s55, s57
	s_cselect_b32 s21, s54, s56
	v_mov_b32_e32 v37, s20
	s_waitcnt lgkmcnt(0)
	v_add_f32_e32 v0, v0, v36
	ds_bpermute_b32 v36, v168, v0
	s_add_u32 s20, s70, s9
	s_waitcnt lgkmcnt(0)
	v_add_f32_e32 v0, v0, v36
	v_mul_f32_e32 v36, v34, v34
	v_mul_f32_e32 v0, v36, v0
	v_fmamk_f32 v0, v0, 0x3c800000, v214
	v_rsq_f32_e32 v0, v0
	v_mov_b32_e32 v36, s21
	s_addc_u32 s21, s71, 0
	v_lshl_add_u64 v[36:37], v[142:143], 2, v[36:37]
	v_mul_f32_e32 v0, v34, v0
	v_mul_f32_e32 v34, v162, v0
	v_lshl_or_b32 v0, v38, 3, s68
	v_or_b32_e32 v38, s58, v0
	v_ashrrev_i32_e32 v39, 31, v38
	v_lshlrev_b64 v[38:39], 19, v[38:39]
	v_lshl_add_u64 v[38:39], s[20:21], 0, v[38:39]
	v_lshlrev_b32_e32 v0, 7, v35
	v_lshl_add_u64 v[46:47], v[38:39], 0, v[0:1]
	s_nop 1
	v_mov_b32_e32 v38, v238
	v_mov_b32_e32 v39, v239
	v_mov_b32_e32 v40, v240
	v_mov_b32_e32 v41, v241
	v_mov_b32_e32 v42, v234
	v_mov_b32_e32 v43, v235
	v_mov_b32_e32 v44, v236
	v_mov_b32_e32 v45, v237
	v_pk_mul_f32 v[40:41], v[40:41], v[34:35] op_sel_hi:[1,0]
	v_pk_mul_f32 v[44:45], v[44:45], v[34:35] op_sel_hi:[1,0]
	v_pk_mul_f32 v[42:43], v[42:43], v[34:35] op_sel_hi:[1,0]
	v_pk_mul_f32 v[38:39], v[38:39], v[34:35] op_sel_hi:[1,0]
	v_pk_mul_f32 v[32:33], v[32:33], v[44:45]
	v_pk_mul_f32 v[30:31], v[30:31], v[42:43]
	v_pk_mul_f32 v[40:41], v[28:29], v[40:41]
	v_pk_mul_f32 v[28:29], v[26:27], v[38:39]
	v_lshl_add_u64 v[38:39], v[142:143], 1, v[46:47]
	v_cvt_pk_bf16_f32 v26, v30, v31
	v_cvt_pk_bf16_f32 v27, v32, v33
	v_cvt_pk_bf16_f32 v28, v28, v29
	v_cvt_pk_bf16_f32 v29, v40, v41
	global_store_dwordx4 v[38:39], v[26:29], off
	s_nop 1
	v_mov_b32_e32 v26, v246
	v_mov_b32_e32 v27, v247
	v_mov_b32_e32 v28, v248
	v_mov_b32_e32 v29, v249
	v_mov_b32_e32 v30, v242
	v_mov_b32_e32 v31, v243
	v_mov_b32_e32 v32, v244
	v_mov_b32_e32 v33, v245
	v_pk_mul_f32 v[28:29], v[28:29], v[34:35] op_sel_hi:[1,0]
	v_pk_mul_f32 v[32:33], v[32:33], v[34:35] op_sel_hi:[1,0]
	v_pk_mul_f32 v[30:31], v[30:31], v[34:35] op_sel_hi:[1,0]
	v_pk_mul_f32 v[26:27], v[26:27], v[34:35] op_sel_hi:[1,0]
	v_pk_mul_f32 v[24:25], v[24:25], v[32:33]
	v_pk_mul_f32 v[22:23], v[22:23], v[30:31]
	v_pk_mul_f32 v[28:29], v[20:21], v[28:29]
	v_pk_mul_f32 v[20:21], v[18:19], v[26:27]
	v_cvt_pk_bf16_f32 v18, v22, v23
	v_cvt_pk_bf16_f32 v19, v24, v25
	v_cvt_pk_bf16_f32 v20, v20, v21
	v_cvt_pk_bf16_f32 v21, v28, v29
	global_store_dwordx4 v[38:39], v[18:21], off offset:64

.LBB0_723:
	s_andn2_b64 vcc, exec, s[20:21]
	s_cbranch_vccnz .LBB0_725
	v_mul_f32_e32 v0, v15, v15
	v_fmac_f32_e32 v0, v14, v14
	v_fmac_f32_e32 v0, v16, v16
	v_fmac_f32_e32 v0, v17, v17
	v_fmac_f32_e32 v0, v10, v10
	v_fmac_f32_e32 v0, v11, v11
	v_fmac_f32_e32 v0, v12, v12
	v_fmac_f32_e32 v0, v13, v13
	v_fmac_f32_e32 v0, v6, v6
	v_fmac_f32_e32 v0, v7, v7
	v_fmac_f32_e32 v0, v8, v8
	v_fmac_f32_e32 v0, v9, v9
	v_pk_mul_f32 v[24:25], v[2:3], v[2:3]
	v_pk_mul_f32 v[20:21], v[4:5], v[4:5]
	v_add_f32_e32 v0, v24, v0
	v_add_f32_e32 v0, v25, v0
	v_add_f32_e32 v0, v20, v0
	v_add_f32_e32 v0, v21, v0
	ds_bpermute_b32 v20, v167, v0
	s_and_b64 s[18:19], s[38:39], exec
	s_cselect_b32 s18, s54, s56
	s_cselect_b32 s11, s55, s57
	v_mov_b32_e32 v21, s11
	s_waitcnt lgkmcnt(0)
	v_add_f32_e32 v0, v0, v20
	ds_bpermute_b32 v20, v168, v0
	s_waitcnt lgkmcnt(0)
	v_add_f32_e32 v0, v0, v20
	v_mul_f32_e32 v20, v18, v18
	v_mul_f32_e32 v0, v20, v0
	v_fmamk_f32 v0, v0, 0x3c800000, v214
	v_rsq_f32_e32 v0, v0
	v_mov_b32_e32 v20, s18
	s_add_u32 s18, s70, s9
	s_addc_u32 s19, s71, 0
	v_mul_f32_e32 v0, v18, v0
	v_mul_f32_e32 v18, v162, v0
	v_lshl_or_b32 v0, v22, 3, s68
	v_or_b32_e32 v22, s58, v0
	v_ashrrev_i32_e32 v23, 31, v22
	v_lshlrev_b64 v[22:23], 19, v[22:23]
	v_lshl_add_u64 v[22:23], s[18:19], 0, v[22:23]
	v_lshlrev_b32_e32 v0, 7, v19
	v_lshl_add_u64 v[20:21], v[142:143], 2, v[20:21]
	v_lshl_add_u64 v[30:31], v[22:23], 0, v[0:1]
	s_nop 1
	v_mov_b32_e32 v22, v238
	v_mov_b32_e32 v23, v239
	v_mov_b32_e32 v24, v240
	v_mov_b32_e32 v25, v241
	v_mov_b32_e32 v26, v234
	v_mov_b32_e32 v27, v235
	v_mov_b32_e32 v28, v236
	v_mov_b32_e32 v29, v237
	v_pk_mul_f32 v[24:25], v[24:25], v[18:19] op_sel_hi:[1,0]
	v_pk_mul_f32 v[28:29], v[28:29], v[18:19] op_sel_hi:[1,0]
	v_pk_mul_f32 v[26:27], v[26:27], v[18:19] op_sel_hi:[1,0]
	v_pk_mul_f32 v[22:23], v[22:23], v[18:19] op_sel_hi:[1,0]
	v_pk_mul_f32 v[16:17], v[16:17], v[28:29]
	v_pk_mul_f32 v[14:15], v[14:15], v[26:27]
	v_pk_mul_f32 v[24:25], v[12:13], v[24:25]
	v_pk_mul_f32 v[12:13], v[10:11], v[22:23]
	v_lshl_add_u64 v[22:23], v[142:143], 1, v[30:31]
	v_cvt_pk_bf16_f32 v10, v14, v15
	v_cvt_pk_bf16_f32 v11, v16, v17
	v_cvt_pk_bf16_f32 v12, v12, v13
	v_cvt_pk_bf16_f32 v13, v24, v25
	global_store_dwordx4 v[22:23], v[10:13], off
	s_nop 1
	v_mov_b32_e32 v10, v246
	v_mov_b32_e32 v11, v247
	v_mov_b32_e32 v12, v248
	v_mov_b32_e32 v13, v249
	v_mov_b32_e32 v14, v242
	v_mov_b32_e32 v15, v243
	v_mov_b32_e32 v16, v244
	v_mov_b32_e32 v17, v245
	v_pk_mul_f32 v[12:13], v[12:13], v[18:19] op_sel_hi:[1,0]
	v_pk_mul_f32 v[16:17], v[16:17], v[18:19] op_sel_hi:[1,0]
	v_pk_mul_f32 v[14:15], v[14:15], v[18:19] op_sel_hi:[1,0]
	v_pk_mul_f32 v[10:11], v[10:11], v[18:19] op_sel_hi:[1,0]
	v_pk_mul_f32 v[8:9], v[8:9], v[16:17]
	v_pk_mul_f32 v[6:7], v[6:7], v[14:15]
	v_pk_mul_f32 v[12:13], v[4:5], v[12:13]
	v_pk_mul_f32 v[4:5], v[2:3], v[10:11]
	v_cvt_pk_bf16_f32 v2, v6, v7
	v_cvt_pk_bf16_f32 v3, v8, v9
	v_cvt_pk_bf16_f32 v4, v4, v5
	v_cvt_pk_bf16_f32 v5, v12, v13
	global_store_dwordx4 v[22:23], v[2:5], off offset:64
